# forget-gate group prefix (p2b): the up-to-eight group totals per lane loaded together instead of one dependent load per loop trip
# baseline (speedup 1.0000x reference)
; __device__ __forceinline__ void p2b_fgroup(Frame& F, const Args& a, int g) {
;     ...
;     const int h = F.tid & 15, part = F.tid >> 4; float s = 0.f;
;     for (int gg = part; gg < g; gg += 32) s += PS[gg * 16 + h];
;     sc[part * 16 + h] = s; __syncthreads();
.LBB0_311:
	v_cmp_gt_i32_e64 s[0:1], s16, v64
	v_mov_b32_e32 v8, 0
	s_and_saveexec_b64 s[4:5], s[0:1]
	s_cbranch_execz .LBB0_315
	v_mov_b32_e32 v8, 0
	v_mov_b32_e32 v2, v6
	v_mov_b32_e32 v9, v64
	s_mov_b64 s[12:13], exec
	v_mov_b32_e32 v18, 0
	v_mov_b32_e32 v19, 0
	v_mov_b32_e32 v20, 0
	v_mov_b32_e32 v21, 0
	v_mov_b32_e32 v22, 0
	v_mov_b32_e32 v23, 0
	v_mov_b32_e32 v24, 0
	v_mov_b32_e32 v25, 0
	v_ashrrev_i32_e32 v3, 31, v2
	v_lshl_add_u64 v[12:13], v[2:3], 2, s[2:3]
	global_load_dword v18, v[12:13], off
	v_add_u32_e32 v9, 32, v9
	v_add_u32_e32 v2, 0x200, v2
	v_cmp_gt_i32_e64 s[0:1], s16, v9
	s_nop 0
	s_and_b64 exec, exec, s[0:1]
	s_cbranch_execz .Lfg_sum
	v_ashrrev_i32_e32 v3, 31, v2
	v_lshl_add_u64 v[12:13], v[2:3], 2, s[2:3]
	global_load_dword v19, v[12:13], off
	v_add_u32_e32 v9, 32, v9
	v_add_u32_e32 v2, 0x200, v2
	v_cmp_gt_i32_e64 s[0:1], s16, v9
	s_nop 0
	s_and_b64 exec, exec, s[0:1]
	s_cbranch_execz .Lfg_sum
	v_ashrrev_i32_e32 v3, 31, v2
	v_lshl_add_u64 v[12:13], v[2:3], 2, s[2:3]
	global_load_dword v20, v[12:13], off
	v_add_u32_e32 v9, 32, v9
	v_add_u32_e32 v2, 0x200, v2
	v_cmp_gt_i32_e64 s[0:1], s16, v9
	s_nop 0
	s_and_b64 exec, exec, s[0:1]
	s_cbranch_execz .Lfg_sum
	v_ashrrev_i32_e32 v3, 31, v2
	v_lshl_add_u64 v[12:13], v[2:3], 2, s[2:3]
	global_load_dword v21, v[12:13], off
	v_add_u32_e32 v9, 32, v9
	v_add_u32_e32 v2, 0x200, v2
	v_cmp_gt_i32_e64 s[0:1], s16, v9
	s_nop 0
	s_and_b64 exec, exec, s[0:1]
	s_cbranch_execz .Lfg_sum
	v_ashrrev_i32_e32 v3, 31, v2
	v_lshl_add_u64 v[12:13], v[2:3], 2, s[2:3]
	global_load_dword v22, v[12:13], off
	v_add_u32_e32 v9, 32, v9
	v_add_u32_e32 v2, 0x200, v2
	v_cmp_gt_i32_e64 s[0:1], s16, v9
	s_nop 0
	s_and_b64 exec, exec, s[0:1]
	s_cbranch_execz .Lfg_sum
	v_ashrrev_i32_e32 v3, 31, v2
	v_lshl_add_u64 v[12:13], v[2:3], 2, s[2:3]
	global_load_dword v23, v[12:13], off
	v_add_u32_e32 v9, 32, v9
	v_add_u32_e32 v2, 0x200, v2
	v_cmp_gt_i32_e64 s[0:1], s16, v9
	s_nop 0
	s_and_b64 exec, exec, s[0:1]
	s_cbranch_execz .Lfg_sum
	v_ashrrev_i32_e32 v3, 31, v2
	v_lshl_add_u64 v[12:13], v[2:3], 2, s[2:3]
	global_load_dword v24, v[12:13], off
	v_add_u32_e32 v9, 32, v9
	v_add_u32_e32 v2, 0x200, v2
	v_cmp_gt_i32_e64 s[0:1], s16, v9
	s_nop 0
	s_and_b64 exec, exec, s[0:1]
	s_cbranch_execz .Lfg_sum
	v_ashrrev_i32_e32 v3, 31, v2
	v_lshl_add_u64 v[12:13], v[2:3], 2, s[2:3]
	global_load_dword v25, v[12:13], off
.Lfg_sum:
	s_mov_b64 exec, s[12:13]
	s_waitcnt vmcnt(0)
	v_add_f32_e32 v8, v8, v18
	v_add_f32_e32 v8, v8, v19
	v_add_f32_e32 v8, v8, v20
	v_add_f32_e32 v8, v8, v21
	v_add_f32_e32 v8, v8, v22
	v_add_f32_e32 v8, v8, v23
	v_add_f32_e32 v8, v8, v24
	v_add_f32_e32 v8, v8, v25
